# nt hint on FoX's read-once Q and gate loads
# speedup vs baseline: 1.0072x; 1.0072x over previous
.LBB0_165:
	s_ashr_i32 s43, s33, 5
	s_lshl_b32 s37, s43, 12
	v_add_u32_e32 v2, s37, v184
	v_ashrrev_i32_e32 v3, 31, v2
	s_bfe_u32 s44, s33, 0x40001
	v_lshlrev_b64 v[2:3], 6, v[2:3]
	v_lshl_add_u64 v[2:3], s[24:25], 0, v[2:3]
	s_lshl_b32 s78, s44, 2
	v_lshl_add_u64 v[2:3], v[2:3], 0, s[78:79]
	s_barrier
	global_load_dword v6, v[2:3], off nt
	global_load_dword v1, v[2:3], off offset:64 nt
	global_load_dword v4, v[2:3], off offset:128 nt
	global_load_dword v5, v[2:3], off offset:192 nt
	global_load_dword v10, v[2:3], off offset:256 nt
	global_load_dword v11, v[2:3], off offset:320 nt
	s_waitcnt lgkmcnt(3)
	global_load_dword v12, v[2:3], off offset:384 nt
	s_nop 0
	global_load_dword v3, v[2:3], off offset:448 nt
	s_waitcnt vmcnt(6)
	v_add_f32_e32 v7, v1, v6
	s_waitcnt vmcnt(5)
	v_add_f32_e32 v8, v4, v7
	s_waitcnt vmcnt(4)
	v_add_f32_e32 v9, v5, v8
	s_waitcnt vmcnt(3)
	v_add_f32_e32 v4, v10, v9
	s_waitcnt vmcnt(2)
	v_add_f32_e32 v5, v11, v4
	s_waitcnt vmcnt(1)
	v_add_f32_e32 v2, v12, v5
	s_waitcnt vmcnt(0)
	v_add_f32_e32 v3, v3, v2
	ds_bpermute_b32 v1, v167, v3
	s_waitcnt lgkmcnt(0)
	v_add_f32_e32 v1, v3, v1
	v_cndmask_b32_e64 v1, v1, v3, s[6:7]
	ds_bpermute_b32 v10, v190, v1
	s_waitcnt lgkmcnt(0)
	v_add_f32_e32 v10, v1, v10
	v_cndmask_b32_e64 v1, v10, v1, s[8:9]
	ds_bpermute_b32 v10, v191, v1
	s_waitcnt lgkmcnt(0)
	v_add_f32_e32 v10, v1, v10
	v_cndmask_b32_e64 v1, v10, v1, s[10:11]
	ds_bpermute_b32 v10, v192, v1
	s_waitcnt lgkmcnt(0)
	v_add_f32_e32 v10, v1, v10
	v_cndmask_b32_e64 v1, v10, v1, s[12:13]
	ds_bpermute_b32 v10, v193, v1
	s_waitcnt lgkmcnt(0)
	v_add_f32_e32 v10, v1, v10
	v_cndmask_b32_e64 v1, v10, v1, s[14:15]
	ds_bpermute_b32 v10, v202, v1
	s_waitcnt lgkmcnt(0)
	v_add_f32_e32 v10, v1, v10
	s_and_saveexec_b64 s[38:39], s[2:3]
	v_mov_b32_e32 v11, s40
	ds_write_b32 v11, v10 offset:16384
	s_or_b64 exec, exec, s[38:39]
	v_cndmask_b32_e64 v1, v10, v1, s[16:17]
	s_andn2_b64 vcc, exec, s[28:29]
	v_sub_f32_e32 v10, v1, v3
	s_waitcnt lgkmcnt(0)
	s_barrier
	s_cbranch_vccnz .LBB0_170
	s_mov_b32 s38, s71
	s_mov_b32 s39, s65

.LBB0_172:
	s_and_b32 s38, s43, 6
	s_xor_b32 s38, s38, 15
	s_and_b32 s37, s43, 1
	s_sub_i32 s38, s38, s42
	s_or_b32 s39, s43, s42
	s_cmp_eq_u32 s37, 0
	s_cselect_b32 s38, s39, s38
	s_lshl_b32 s44, s38, 8
	v_add_u32_e32 v182, s44, v205
	v_ashrrev_i32_e32 v183, 31, v182
	v_and_b32_e32 v2, 0xfe0, v182
	v_mov_b32_e32 v3, v0
	v_lshlrev_b64 v[2:3], 7, v[2:3]
	v_lshl_add_u64 v[2:3], v[176:177], 0, v[2:3]
	global_load_dwordx4 v[66:69], v[2:3], off nt
	global_load_dwordx4 v[70:73], v[2:3], off offset:1024 nt
	global_load_dwordx4 v[74:77], v[2:3], off offset:2048 nt
	global_load_dwordx4 v[78:81], v[2:3], off offset:3072 nt
	v_mov_b32_e32 v1, 0x3f80
	v_cndmask_b32_e64 v196, 0, v1, s[16:17]
	v_mov_b32_e32 v197, v0
	v_mov_b32_e32 v198, v0
	v_mov_b32_e32 v199, v0
	v_mov_b32_e32 v162, v0
	v_mov_b32_e32 v163, v0
	v_mov_b32_e32 v164, v0
	v_mov_b32_e32 v165, v0
	s_andn2_b64 vcc, exec, s[30:31]
	s_cbranch_vccnz .LBB0_174
	s_nop 0
